# attention loop: one workgroup barrier per KV tile (K tile written before B1, V after), plus per-MFMA counted LDS waits in PV
# speedup vs baseline: 1.0036x; 1.0036x over previous
; #define SBAR() __builtin_amdgcn_sched_barrier(0)
; #define SLOAD(i, k0) do { sr_[i].vs0 = ld8(&Vh[(long)((k0) + sr) * LDK + sc]); sr_[i].vs1 = ld8(&Vh[(long)((k0) + 32 + sr) * LDK + sc]); \
;     sr_[i].ks0 = ld8(&Kh[(long)((k0) + sr) * LDK + sc]); sr_[i].ks1 = ld8(&Kh[(long)((k0) + 32 + sr) * LDK + sc]); } while (0)
; DI void finishSM(f32x16& p0, f32x16& p1, float alpha, float& l_reg, bf16x8& pa0, bf16x8& pa1, bf16x8& pa2, bf16x8& pa3) {
;   for (int r = 0; r < 16; ++r) p1[r] = __builtin_amdgcn_exp2f(p1[r]);
;   float ps = 0; for (int r = 0; r < 16; ++r) ps += p0[r]; for (int r = 0; r < 16; ++r) ps += p1[r];
;   { auto rr = __builtin_amdgcn_permlane32_swap(__float_as_uint(ps), __float_as_uint(ps), false, false);
;     ps = __uint_as_float(rr[0]) + __uint_as_float(rr[1]); }
;   l_reg = l_reg * alpha + ps;
;     ...
;   PK4(p0, 0, pa0); PK4(p0, 8, pa1); PK4(p1, 0, pa2); PK4(p1, 8, pa3);
;     ...
; }
; DI void qkt(f32x16& p0, f32x16& p1, const bf16_t* Ks, const bf16x8* qr, int r32, int hi) {
;   p0 = f32x16{}; p1 = f32x16{};
;   for (int d0 = 0; d0 < 8; ++d0) { int cb = (d0 * 16 + hi * 8) * 2;
;     bf16x8 b0 = *reinterpret_cast<const bf16x8*>((const char*)Ks + KSWZ(r32, cb));
;     bf16x8 b1 = *reinterpret_cast<const bf16x8*>((const char*)Ks + KSWZ(32 + r32, cb));
;     p0 = __builtin_amdgcn_mfma_f32_32x32x16_bf16(b0, qr[d0], p0, 0, 0, 0);
;     p1 = __builtin_amdgcn_mfma_f32_32x32x16_bf16(b1, qr[d0], p1, 0, 0, 0); }
; }
; DI void attn_dense_body(const bf16_t* __restrict__ Qb, const bf16_t* __restrict__ Kh, const bf16_t* __restrict__ Vh, ...
;     ...
;     SBAR(); qkt(pB0, pB1, (bf16_t*)((char*)K_lds + SHM_K), qr, r32, hi);
;     finishSM(pA0, pA1, alA, l_reg, pa0, pa1, pa2, pa3); SBAR();
;     SLOAD(SO, (j + 2) * KVBLK); SBAR();
;     pv_d0(o, vb0, pa0, pa1, pa2, pa3); partialSM(pB0, pB1, m_reg, mnB, alB);
.LBB0_835:
	ds_read_b128 v[64:67], v207 offset:49152
	ds_read_b128 v[68:71], v207 offset:57344
	ds_read_b128 v[232:235], v210 offset:49152
	ds_read_b128 v[236:239], v210 offset:57344
	v_add_f32_e32 v160, 0, v161
	v_add_f32_e32 v160, v175, v160
	s_waitcnt lgkmcnt(3)
	v_mfma_f32_32x32x16_bf16 v[80:95], v[64:67], v[116:119], 0
	v_add_f32_e32 v160, v162, v160
	v_add_f32_e32 v160, v219, v160
	v_add_f32_e32 v160, v174, v160
	v_add_f32_e32 v160, v222, v160
	v_add_f32_e32 v160, v163, v160
	v_add_f32_e32 v160, v173, v160
	v_add_f32_e32 v160, v164, v160
	s_waitcnt lgkmcnt(2)
	v_mfma_f32_32x32x16_bf16 v[64:79], v[68:71], v[116:119], 0
	v_add_f32_e32 v160, v171, v160
	v_add_f32_e32 v160, v165, v160
	v_add_f32_e32 v160, v172, v160
	v_exp_f32_e32 v158, v158
	v_add_f32_e32 v160, v166, v160
	v_exp_f32_e32 v159, v159
	v_add_f32_e32 v160, v169, v160
	s_waitcnt lgkmcnt(1)
	v_mfma_f32_32x32x16_bf16 v[80:95], v[232:235], v[124:127], v[80:95]
	v_exp_f32_e32 v156, v156
	v_add_f32_e32 v160, v167, v160
	v_exp_f32_e32 v157, v157
	v_add_f32_e32 v160, v170, v160
	v_exp_f32_e32 v152, v152
	v_add_f32_e32 v160, v158, v160
	v_exp_f32_e32 v153, v153
	s_waitcnt lgkmcnt(0)
	v_mfma_f32_32x32x16_bf16 v[64:79], v[236:239], v[124:127], v[64:79]
	ds_read_b128 v[232:235], v211 offset:49152
	ds_read_b128 v[236:239], v211 offset:57344
	v_add_f32_e32 v160, v159, v160
	v_exp_f32_e32 v148, v148
	v_add_f32_e32 v160, v156, v160
	v_exp_f32_e32 v149, v149
	v_add_f32_e32 v160, v157, v160
	v_exp_f32_e32 v146, v146
	s_waitcnt lgkmcnt(1)
	v_mfma_f32_32x32x16_bf16 v[80:95], v[232:235], v[120:123], v[80:95]
	v_add_f32_e32 v160, v152, v160
	v_exp_f32_e32 v147, v147
	v_add_f32_e32 v160, v153, v160
	v_exp_f32_e32 v154, v154
	v_add_f32_e32 v160, v148, v160
	v_exp_f32_e32 v155, v155
	v_add_f32_e32 v160, v149, v160
	s_waitcnt lgkmcnt(0)
	v_mfma_f32_32x32x16_bf16 v[64:79], v[236:239], v[120:123], v[64:79]
	ds_read_b128 v[232:235], v208 offset:49152
	ds_read_b128 v[236:239], v208 offset:57344
	v_exp_f32_e32 v150, v150
	v_add_f32_e32 v160, v146, v160
	v_exp_f32_e32 v151, v151
	v_add_f32_e32 v160, v147, v160
	v_exp_f32_e32 v144, v144
	v_add_f32_e32 v160, v154, v160
	s_waitcnt lgkmcnt(1)
	v_mfma_f32_32x32x16_bf16 v[80:95], v[232:235], v[112:115], v[80:95]
	v_exp_f32_e32 v145, v145
	v_add_f32_e32 v160, v155, v160
	v_add_f32_e32 v160, v150, v160
	v_add_f32_e32 v160, v151, v160
	v_add_f32_e32 v160, v144, v160
	v_add_f32_e32 v216, v145, v160
	v_mov_b32_e32 v217, v216
	s_waitcnt lgkmcnt(0)
	v_mfma_f32_32x32x16_bf16 v[64:79], v[236:239], v[112:115], v[64:79]
	ds_read_b128 v[232:235], v209 offset:49152
	ds_read_b128 v[236:239], v209 offset:57344
	v_permlane32_swap_b32_e32 v216, v217
	s_waitcnt lgkmcnt(1)
	v_mfma_f32_32x32x16_bf16 v[80:95], v[232:235], v[108:111], v[80:95]
	s_waitcnt lgkmcnt(0)
	v_mfma_f32_32x32x16_bf16 v[64:79], v[236:239], v[108:111], v[64:79]
	ds_read_b128 v[232:235], v212 offset:49152
	ds_read_b128 v[236:239], v212 offset:57344
	s_waitcnt lgkmcnt(1)
	v_mfma_f32_32x32x16_bf16 v[80:95], v[232:235], v[104:107], v[80:95]
	s_waitcnt lgkmcnt(0)
	v_mfma_f32_32x32x16_bf16 v[64:79], v[236:239], v[104:107], v[64:79]
	ds_read_b128 v[232:235], v213 offset:49152
	ds_read_b128 v[236:239], v213 offset:57344
	s_waitcnt lgkmcnt(1)
	v_mfma_f32_32x32x16_bf16 v[80:95], v[232:235], v[100:103], v[80:95]
	s_waitcnt lgkmcnt(0)
	v_mfma_f32_32x32x16_bf16 v[64:79], v[236:239], v[100:103], v[64:79]
	ds_read_b128 v[232:235], v214 offset:49152
	ds_read_b128 v[236:239], v214 offset:57344
	v_cvt_pk_bf16_f32 v160, v161, v175
	v_cvt_pk_bf16_f32 v161, v162, v219
	v_cvt_pk_bf16_f32 v162, v174, v222
	v_cvt_pk_bf16_f32 v163, v163, v173
	v_cvt_pk_bf16_f32 v164, v164, v171
	v_cvt_pk_bf16_f32 v165, v165, v172
	s_waitcnt lgkmcnt(1)
	v_mfma_f32_32x32x16_bf16 v[80:95], v[232:235], v[96:99], v[80:95]
	v_cvt_pk_bf16_f32 v166, v166, v169
	v_cvt_pk_bf16_f32 v167, v167, v170
	v_cvt_pk_bf16_f32 v170, v158, v159
	v_cvt_pk_bf16_f32 v171, v156, v157
	v_cvt_pk_bf16_f32 v172, v152, v153
	v_cvt_pk_bf16_f32 v173, v148, v149
	v_cvt_pk_bf16_f32 v218, v146, v147
	s_waitcnt lgkmcnt(0)
	v_mfma_f32_32x32x16_bf16 v[64:79], v[236:239], v[96:99], v[64:79]
	v_cvt_pk_bf16_f32 v219, v154, v155
	v_cvt_pk_bf16_f32 v220, v150, v151
	v_permlane32_swap_b32_e32 v160, v162
	v_cvt_pk_bf16_f32 v221, v144, v145
	v_permlane32_swap_b32_e32 v218, v220
	v_permlane32_swap_b32_e32 v161, v163
	v_permlane32_swap_b32_e32 v164, v166
	v_permlane32_swap_b32_e32 v165, v167
	v_permlane32_swap_b32_e32 v170, v172
	v_permlane32_swap_b32_e32 v171, v173
	v_permlane32_swap_b32_e32 v219, v221
	s_waitcnt vmcnt(0)
	ds_write_b128 v203, v[132:135] offset:32768
	ds_write_b128 v206, v[140:143] offset:32768
	s_mov_b32 s0, 0xffff4000
	v_add_co_u32_e32 v144, vcc, s0, v194
	s_movk_i32 s0, 0x8000
	s_nop 0
	v_addc_co_u32_e32 v145, vcc, -1, v195, vcc
	v_add_co_u32_e32 v148, vcc, s0, v194
	s_mov_b32 s0, 0xfeef4000
	s_nop 0
	v_addc_co_u32_e32 v149, vcc, -1, v195, vcc
	v_add_co_u32_e32 v152, vcc, s0, v194
	s_mov_b32 s0, 0xfeef8000
	s_nop 0
	v_addc_co_u32_e32 v153, vcc, -1, v195, vcc
	v_add_co_u32_e32 v156, vcc, s0, v194
	global_load_dwordx4 v[144:147], v[144:145], off
	s_nop 0
	global_load_dwordx4 v[148:151], v[148:149], off
	v_addc_co_u32_e32 v157, vcc, -1, v195, vcc
	global_load_dwordx4 v[152:155], v[152:153], off
	s_nop 0
	global_load_dwordx4 v[156:159], v[156:157], off
	ds_read_b64_tr_b16 v[232:233], v202 offset:0
	ds_read_b64_tr_b16 v[234:235], v202 offset:0x800
	ds_read_b64_tr_b16 v[236:237], v202 offset:0x1000
	ds_read_b64_tr_b16 v[238:239], v202 offset:0x1800
	ds_read_b64_tr_b16 v[240:241], v202 offset:0x2000
	ds_read_b64_tr_b16 v[242:243], v202 offset:0x2800
	ds_read_b64_tr_b16 v[244:245], v202 offset:0x3000
	ds_read_b64_tr_b16 v[246:247], v202 offset:0x3800
	s_waitcnt lgkmcnt(6)
; #define SBAR() __builtin_amdgcn_sched_barrier(0)
; DI void partialSM(f32x16& p0, f32x16& p1, float& m_reg, float& mn, float& alpha) {
;   constexpr float C = SCALE * 1.4426950408889634f;
;   float pmax = p0[0]; for (int r = 1; r < 16; ++r) pmax = fmaxf(pmax, p0[r]); for (int r = 0; r < 16; ++r) pmax = fmaxf(pmax, p1[r]);
;   { auto rr = __builtin_amdgcn_permlane32_swap(__float_as_uint(pmax), __float_as_uint(pmax), false, false);
;     pmax = fmaxf(__uint_as_float(rr[0]), __uint_as_float(rr[1])); }
;   if (__builtin_expect(__all(pmax - m_reg <= THR / SCALE), 1)) { mn = m_reg; alpha = 1.f; }
;   else { mn = fmaxf(m_reg, pmax); alpha = __builtin_amdgcn_exp2f((m_reg - mn) * C); m_reg = mn; }
;   float mnC = -mn * C;
;   for (int r = 0; r < 16; ++r) p0[r] = fmaf(p0[r], C, mnC); for (int r = 0; r < 16; ++r) p1[r] = fmaf(p1[r], C, mnC);
;   for (int r = 0; r < 16; ++r) p0[r] = __builtin_amdgcn_exp2f(p0[r]);
; }
; template <int D0> DI void pv_one(f32x16& od, int vb, bf16x8 pa0, bf16x8 pa1, bf16x8 pa2, bf16x8 pa3) {
;   const s16x4 l0 = tr_read<v_rd_off(D0, 0, 0)>(vb), h0 = tr_read<v_rd_off(D0, 0, 1)>(vb), l1 = tr_read<v_rd_off(D0, 1, 0)>(vb), h1 = tr_read<v_rd_off(D0, 1, 1)>(vb);
;   const s16x4 l2 = tr_read<v_rd_off(D0, 2, 0)>(vb), h2 = tr_read<v_rd_off(D0, 2, 1)>(vb), l3 = tr_read<v_rd_off(D0, 3, 0)>(vb), h3 = tr_read<v_rd_off(D0, 3, 1)>(vb);
;   asm volatile("s_waitcnt lgkmcnt(0)" ::: "memory"); SBAR();
;     ...
;   od = __builtin_amdgcn_mfma_f32_32x32x16_bf16(pa0, PK(l0, h0), od, 0, 0, 0);
;   od = __builtin_amdgcn_mfma_f32_32x32x16_bf16(pa1, PK(l1, h1), od, 0, 0, 0);
;   od = __builtin_amdgcn_mfma_f32_32x32x16_bf16(pa2, PK(l2, h2), od, 0, 0, 0);
;   od = __builtin_amdgcn_mfma_f32_32x32x16_bf16(pa3, PK(l3, h3), od, 0, 0, 0);
;     ...
; }
; DI void pv_d0(f32x16* o, int vb, bf16x8 pa0, bf16x8 pa1, bf16x8 pa2, bf16x8 pa3) {
;   pv_one<0>(o[0], vb, pa0, pa1, pa2, pa3); pv_one<1>(o[1], vb, pa0, pa1, pa2, pa3); pv_one<2>(o[2], vb, pa0, pa1, pa2, pa3); pv_one<3>(o[3], vb, pa0, pa1, pa2, pa3);
; }
	s_nop 0
	v_mfma_f32_32x32x16_bf16 v[0:15], v[160:163], v[232:235], v[0:15]
	ds_read_b64_tr_b16 v[232:233], v202 offset:0x200
	ds_read_b64_tr_b16 v[234:235], v202 offset:0xa00
	s_waitcnt lgkmcnt(6)
	v_mfma_f32_32x32x16_bf16 v[0:15], v[164:167], v[236:239], v[0:15]
	ds_read_b64_tr_b16 v[236:237], v202 offset:0x1200
	ds_read_b64_tr_b16 v[238:239], v202 offset:0x1a00
	s_waitcnt lgkmcnt(6)
	v_mfma_f32_32x32x16_bf16 v[0:15], v[170:173], v[240:243], v[0:15]
	ds_read_b64_tr_b16 v[240:241], v202 offset:0x2200
	ds_read_b64_tr_b16 v[242:243], v202 offset:0x2a00
	s_waitcnt lgkmcnt(6)
	v_mfma_f32_32x32x16_bf16 v[0:15], v[218:221], v[244:247], v[0:15]
	ds_read_b64_tr_b16 v[244:245], v202 offset:0x3200
	ds_read_b64_tr_b16 v[246:247], v202 offset:0x3a00
	s_waitcnt lgkmcnt(6)
	v_mfma_f32_32x32x16_bf16 v[48:63], v[160:163], v[232:235], v[48:63]
	ds_read_b64_tr_b16 v[232:233], v202 offset:0x400
	ds_read_b64_tr_b16 v[234:235], v202 offset:0xc00
	s_waitcnt lgkmcnt(6)
	v_mfma_f32_32x32x16_bf16 v[48:63], v[164:167], v[236:239], v[48:63]
	ds_read_b64_tr_b16 v[236:237], v202 offset:0x1400
	ds_read_b64_tr_b16 v[238:239], v202 offset:0x1c00
	s_waitcnt lgkmcnt(6)
	v_mfma_f32_32x32x16_bf16 v[48:63], v[170:173], v[240:243], v[48:63]
	ds_read_b64_tr_b16 v[240:241], v202 offset:0x2400
	ds_read_b64_tr_b16 v[242:243], v202 offset:0x2c00
	s_waitcnt lgkmcnt(6)
	v_mfma_f32_32x32x16_bf16 v[48:63], v[218:221], v[244:247], v[48:63]
	ds_read_b64_tr_b16 v[244:245], v202 offset:0x3400
	ds_read_b64_tr_b16 v[246:247], v202 offset:0x3c00
	s_waitcnt lgkmcnt(6)
	v_mfma_f32_32x32x16_bf16 v[32:47], v[160:163], v[232:235], v[32:47]
	ds_read_b64_tr_b16 v[232:233], v202 offset:0x600
	ds_read_b64_tr_b16 v[234:235], v202 offset:0xe00
	s_waitcnt lgkmcnt(6)
	v_mfma_f32_32x32x16_bf16 v[32:47], v[164:167], v[236:239], v[32:47]
	ds_read_b64_tr_b16 v[236:237], v202 offset:0x1600
	ds_read_b64_tr_b16 v[238:239], v202 offset:0x1e00
	s_waitcnt lgkmcnt(6)
	v_mfma_f32_32x32x16_bf16 v[32:47], v[170:173], v[240:243], v[32:47]
	ds_read_b64_tr_b16 v[240:241], v202 offset:0x2600
	ds_read_b64_tr_b16 v[242:243], v202 offset:0x2e00
	s_waitcnt lgkmcnt(6)
	v_mfma_f32_32x32x16_bf16 v[32:47], v[218:221], v[244:247], v[32:47]
	ds_read_b64_tr_b16 v[244:245], v202 offset:0x3600
	ds_read_b64_tr_b16 v[246:247], v202 offset:0x3e00
	s_waitcnt lgkmcnt(6)
	v_mfma_f32_32x32x16_bf16 v[16:31], v[160:163], v[232:235], v[16:31]
	v_max_f32_e32 v160, v81, v81
	v_max_f32_e32 v161, v80, v80
	v_max_f32_e32 v160, v161, v160
	v_max3_f32 v160, v160, v82, v83
	v_max3_f32 v160, v160, v84, v85
	v_max3_f32 v160, v160, v86, v87
	v_max3_f32 v160, v160, v88, v89
	v_max3_f32 v160, v160, v90, v91
	v_max3_f32 v160, v160, v92, v93
	s_waitcnt lgkmcnt(4)
	v_mfma_f32_32x32x16_bf16 v[16:31], v[164:167], v[236:239], v[16:31]
	v_max3_f32 v160, v160, v94, v95
	v_max3_f32 v160, v160, v64, v65
	v_max3_f32 v160, v160, v66, v67
	v_max3_f32 v160, v160, v68, v69
	v_max3_f32 v160, v160, v70, v71
	v_max3_f32 v160, v160, v72, v73
	v_max3_f32 v160, v160, v74, v75
	v_max3_f32 v160, v160, v76, v77
	s_waitcnt lgkmcnt(2)
	v_mfma_f32_32x32x16_bf16 v[16:31], v[170:173], v[240:243], v[16:31]
	v_max3_f32 v160, v160, v78, v79
	v_mov_b32_e32 v161, v160
	s_nop 1
	v_permlane32_swap_b32_e32 v160, v161
	v_max_f32_e32 v161, v161, v161
	v_max_f32_e32 v160, v160, v160
	v_max_f32_e32 v160, v160, v161
	v_sub_f32_e32 v161, v160, v168
	v_cmp_ge_f32_e32 vcc, s95, v161
	v_max_f32_e32 v161, v168, v168
	v_max_f32_e32 v160, v161, v160
	s_waitcnt lgkmcnt(0)
	v_mfma_f32_32x32x16_bf16 v[16:31], v[218:221], v[244:247], v[16:31]
	v_sub_f32_e32 v161, v168, v160
	v_mul_f32_e32 v161, 0x3e0293ee, v161
	v_exp_f32_e32 v161, v161
	s_cmp_eq_u64 vcc, exec
	s_cselect_b64 s[0:1], -1, 0
	s_barrier
	s_waitcnt vmcnt(4)
	v_cndmask_b32_e64 v218, v161, 1.0, s[0:1]
	v_cmp_gt_f32_e32 vcc, 1.0, v218
	s_waitcnt vmcnt(7)
	ds_write_b128 v204, v[128:131]
	s_waitcnt vmcnt(6)
	ds_write_b128 v205, v[136:139]
	s_cbranch_vccz .LBB0_839
	s_and_saveexec_b64 s[10:11], s[4:5]
	ds_write_b32 v199, v218 offset:128
	s_or_b64 exec, exec, s[10:11]
	s_waitcnt lgkmcnt(0)
	v_add_u32_e32 v161, v198, v180
	ds_read_b128 v[162:165], v161 offset:224
	ds_read_b128 v[170:173], v161 offset:192
	ds_read_b128 v[220:223], v161 offset:160
	ds_read_b128 v[232:235], v161 offset:128
	s_waitcnt lgkmcnt(3)
	v_pk_mul_f32 v[12:13], v[12:13], v[162:163]
	s_waitcnt lgkmcnt(2)
	v_pk_mul_f32 v[8:9], v[8:9], v[170:171]
	s_waitcnt lgkmcnt(1)
	v_pk_mul_f32 v[4:5], v[4:5], v[220:221]
	v_pk_mul_f32 v[14:15], v[14:15], v[164:165]
	v_pk_mul_f32 v[10:11], v[10:11], v[172:173]
	v_pk_mul_f32 v[6:7], v[6:7], v[222:223]
	s_waitcnt lgkmcnt(0)
	v_pk_mul_f32 v[2:3], v[2:3], v[234:235]
	v_pk_mul_f32 v[0:1], v[0:1], v[232:233]
	v_pk_mul_f32 v[60:61], v[60:61], v[162:163]
	v_pk_mul_f32 v[56:57], v[56:57], v[170:171]
	v_pk_mul_f32 v[52:53], v[52:53], v[220:221]
	v_pk_mul_f32 v[62:63], v[62:63], v[164:165]
	v_pk_mul_f32 v[58:59], v[58:59], v[172:173]
	v_pk_mul_f32 v[54:55], v[54:55], v[222:223]
	v_pk_mul_f32 v[50:51], v[50:51], v[234:235]
	v_pk_mul_f32 v[48:49], v[48:49], v[232:233]
	v_pk_mul_f32 v[44:45], v[44:45], v[162:163]
	v_pk_mul_f32 v[40:41], v[40:41], v[170:171]
	v_pk_mul_f32 v[36:37], v[36:37], v[220:221]
	v_pk_mul_f32 v[46:47], v[46:47], v[164:165]
	v_pk_mul_f32 v[42:43], v[42:43], v[172:173]
	v_pk_mul_f32 v[38:39], v[38:39], v[222:223]
	v_pk_mul_f32 v[34:35], v[34:35], v[234:235]
	v_pk_mul_f32 v[32:33], v[32:33], v[232:233]
	v_pk_mul_f32 v[28:29], v[28:29], v[162:163]
	v_pk_mul_f32 v[24:25], v[24:25], v[170:171]
	v_pk_mul_f32 v[20:21], v[20:21], v[220:221]
	v_pk_mul_f32 v[30:31], v[30:31], v[164:165]
	v_pk_mul_f32 v[26:27], v[26:27], v[172:173]
	v_pk_mul_f32 v[22:23], v[22:23], v[222:223]
	v_pk_mul_f32 v[18:19], v[18:19], v[234:235]
	v_pk_mul_f32 v[16:17], v[16:17], v[232:233]
; DI void partialSM(f32x16& p0, f32x16& p1, float& m_reg, float& mn, float& alpha) {
;   constexpr float C = SCALE * 1.4426950408889634f;
;   float pmax = p0[0]; for (int r = 1; r < 16; ++r) pmax = fmaxf(pmax, p0[r]); for (int r = 0; r < 16; ++r) pmax = fmaxf(pmax, p1[r]);
;   { auto rr = __builtin_amdgcn_permlane32_swap(__float_as_uint(pmax), __float_as_uint(pmax), false, false);
;     pmax = fmaxf(__uint_as_float(rr[0]), __uint_as_float(rr[1])); }
;   if (__builtin_expect(__all(pmax - m_reg <= THR / SCALE), 1)) { mn = m_reg; alpha = 1.f; }
;   else { mn = fmaxf(m_reg, pmax); alpha = __builtin_amdgcn_exp2f((m_reg - mn) * C); m_reg = mn; }
;   float mnC = -mn * C;
;   for (int r = 0; r < 16; ++r) p0[r] = fmaf(p0[r], C, mnC); for (int r = 0; r < 16; ++r) p1[r] = fmaf(p1[r], C, mnC);
;   for (int r = 0; r < 16; ++r) p0[r] = __builtin_amdgcn_exp2f(p0[r]);
; }
; DI void finishSM(f32x16& p0, f32x16& p1, float alpha, float& l_reg, bf16x8& pa0, bf16x8& pa1, bf16x8& pa2, bf16x8& pa3) {
;   for (int r = 0; r < 16; ++r) p1[r] = __builtin_amdgcn_exp2f(p1[r]);
;   float ps = 0; for (int r = 0; r < 16; ++r) ps += p0[r]; for (int r = 0; r < 16; ++r) ps += p1[r];
;   { auto rr = __builtin_amdgcn_permlane32_swap(__float_as_uint(ps), __float_as_uint(ps), false, false);
;     ps = __uint_as_float(rr[0]) + __uint_as_float(rr[1]); }
;   l_reg = l_reg * alpha + ps;
;     ...
;   PK4(p0, 0, pa0); PK4(p0, 8, pa1); PK4(p1, 0, pa2); PK4(p1, 8, pa3);
;     ...
; }
; DI void qkt(f32x16& p0, f32x16& p1, const bf16_t* Ks, const bf16x8* qr, int r32, int hi) {
;   p0 = f32x16{}; p1 = f32x16{};
;   for (int d0 = 0; d0 < 8; ++d0) { int cb = (d0 * 16 + hi * 8) * 2;
;     bf16x8 b0 = *reinterpret_cast<const bf16x8*>((const char*)Ks + KSWZ(r32, cb));
;     bf16x8 b1 = *reinterpret_cast<const bf16x8*>((const char*)Ks + KSWZ(32 + r32, cb));
;     p0 = __builtin_amdgcn_mfma_f32_32x32x16_bf16(b0, qr[d0], p0, 0, 0, 0);
;     p1 = __builtin_amdgcn_mfma_f32_32x32x16_bf16(b1, qr[d0], p1, 0, 0, 0); }
; }
.LBB0_839:
	v_cndmask_b32_e64 v219, v160, v168, s[0:1]
	v_mul_f32_e32 v220, 0xbe0293ee, v219
	v_fmamk_f32 v80, v80, 0x3e0293ee, v220
	v_fmamk_f32 v81, v81, 0x3e0293ee, v220
	v_fmamk_f32 v82, v82, 0x3e0293ee, v220
	v_fmamk_f32 v83, v83, 0x3e0293ee, v220
	v_fmamk_f32 v84, v84, 0x3e0293ee, v220
	v_fmamk_f32 v85, v85, 0x3e0293ee, v220
	v_fmamk_f32 v86, v86, 0x3e0293ee, v220
	v_fmamk_f32 v87, v87, 0x3e0293ee, v220
	v_fmamk_f32 v88, v88, 0x3e0293ee, v220
	v_fmamk_f32 v89, v89, 0x3e0293ee, v220
	v_fmamk_f32 v90, v90, 0x3e0293ee, v220
	v_fmamk_f32 v91, v91, 0x3e0293ee, v220
	v_fmamk_f32 v92, v92, 0x3e0293ee, v220
	v_fmamk_f32 v93, v93, 0x3e0293ee, v220
	v_fmamk_f32 v94, v94, 0x3e0293ee, v220
	v_fmamk_f32 v95, v95, 0x3e0293ee, v220
	v_exp_f32_e32 v160, v80
	v_exp_f32_e32 v175, v81
	v_exp_f32_e32 v161, v82
	v_exp_f32_e32 v174, v83
	v_exp_f32_e32 v162, v84
	v_exp_f32_e32 v173, v85
	v_exp_f32_e32 v163, v86
	v_exp_f32_e32 v172, v87
	v_exp_f32_e32 v164, v88
	v_exp_f32_e32 v171, v89
	v_exp_f32_e32 v165, v90
	v_exp_f32_e32 v170, v91
	v_exp_f32_e32 v166, v92
	v_exp_f32_e32 v169, v93
	v_exp_f32_e32 v167, v94
	v_exp_f32_e32 v168, v95
	v_fmamk_f32 v236, v64, 0x3e0293ee, v220
	v_fmamk_f32 v237, v65, 0x3e0293ee, v220
	v_fmamk_f32 v238, v66, 0x3e0293ee, v220
	v_fmamk_f32 v239, v67, 0x3e0293ee, v220
	v_fmamk_f32 v240, v68, 0x3e0293ee, v220
	v_fmamk_f32 v222, v69, 0x3e0293ee, v220
	v_fmamk_f32 v223, v70, 0x3e0293ee, v220
	v_fmamk_f32 v231, v71, 0x3e0293ee, v220
	v_fmamk_f32 v232, v72, 0x3e0293ee, v220
	v_fmamk_f32 v233, v73, 0x3e0293ee, v220
	v_fmamk_f32 v234, v74, 0x3e0293ee, v220
	v_fmamk_f32 v235, v75, 0x3e0293ee, v220
	v_fmamk_f32 v221, v76, 0x3e0293ee, v220
	v_fmamk_f32 v241, v77, 0x3e0293ee, v220
	v_fmamk_f32 v242, v78, 0x3e0293ee, v220
	v_fmac_f32_e32 v220, 0x3e0293ee, v79
	s_waitcnt lgkmcnt(0)
	ds_read_b128 v[64:67], v207 offset:32768
	ds_read_b128 v[68:71], v207 offset:40960
	ds_read_b128 v[244:247], v210 offset:32768
	ds_read_b128 v[248:251], v210 offset:40960
	v_exp_f32_e32 v226, v238
	v_exp_f32_e32 v238, v220
	s_waitcnt lgkmcnt(3)
	v_mfma_f32_32x32x16_bf16 v[80:95], v[64:67], v[116:119], 0
	v_add_f32_e32 v220, 0, v160
	v_add_f32_e32 v220, v175, v220
	v_add_f32_e32 v220, v161, v220
	v_add_f32_e32 v220, v174, v220
	v_add_f32_e32 v220, v162, v220
	v_add_f32_e32 v220, v173, v220
	v_add_f32_e32 v220, v163, v220
	s_waitcnt lgkmcnt(2)
	v_mfma_f32_32x32x16_bf16 v[64:79], v[68:71], v[116:119], 0
	v_add_f32_e32 v220, v172, v220
	v_add_f32_e32 v220, v164, v220
	v_add_f32_e32 v220, v171, v220
	v_add_f32_e32 v220, v165, v220
	v_add_f32_e32 v220, v170, v220
	v_exp_f32_e32 v224, v236
	v_add_f32_e32 v220, v166, v220
	s_waitcnt lgkmcnt(1)
	v_mfma_f32_32x32x16_bf16 v[80:95], v[244:247], v[124:127], v[80:95]
	v_exp_f32_e32 v225, v237
	v_add_f32_e32 v220, v169, v220
	v_add_f32_e32 v220, v167, v220
	v_exp_f32_e32 v227, v239
	v_add_f32_e32 v220, v168, v220
	v_exp_f32_e32 v228, v240
	v_add_f32_e32 v220, v224, v220
	s_waitcnt lgkmcnt(0)
	v_mfma_f32_32x32x16_bf16 v[64:79], v[248:251], v[124:127], v[64:79]
	ds_read_b128 v[244:247], v211 offset:32768
	ds_read_b128 v[248:251], v211 offset:40960
	v_exp_f32_e32 v222, v222
	v_add_f32_e32 v220, v225, v220
	v_exp_f32_e32 v223, v223
	v_add_f32_e32 v220, v226, v220
	v_exp_f32_e32 v229, v231
	v_add_f32_e32 v220, v227, v220
	s_waitcnt lgkmcnt(1)
	v_mfma_f32_32x32x16_bf16 v[80:95], v[244:247], v[120:123], v[80:95]
	v_exp_f32_e32 v231, v232
	v_add_f32_e32 v220, v228, v220
	v_exp_f32_e32 v232, v233
	v_add_f32_e32 v220, v222, v220
	v_exp_f32_e32 v233, v234
	v_add_f32_e32 v220, v223, v220
	v_exp_f32_e32 v234, v235
	s_waitcnt lgkmcnt(0)
	v_mfma_f32_32x32x16_bf16 v[64:79], v[248:251], v[120:123], v[64:79]
	ds_read_b128 v[244:247], v208 offset:32768
	ds_read_b128 v[248:251], v208 offset:40960
	v_add_f32_e32 v220, v229, v220
	v_exp_f32_e32 v235, v221
	v_add_f32_e32 v220, v231, v220
	v_exp_f32_e32 v236, v241
	v_add_f32_e32 v220, v232, v220
	v_exp_f32_e32 v237, v242
	s_waitcnt lgkmcnt(1)
	v_mfma_f32_32x32x16_bf16 v[80:95], v[244:247], v[112:115], v[80:95]
	v_add_f32_e32 v220, v233, v220
	v_add_f32_e32 v220, v234, v220
	v_add_f32_e32 v220, v235, v220
	v_add_f32_e32 v220, v236, v220
	v_add_f32_e32 v220, v237, v220
	v_add_f32_e32 v220, v238, v220
	v_mov_b32_e32 v221, v220
	s_waitcnt lgkmcnt(0)
	v_mfma_f32_32x32x16_bf16 v[64:79], v[248:251], v[112:115], v[64:79]
	ds_read_b128 v[244:247], v209 offset:32768
	ds_read_b128 v[248:251], v209 offset:40960
	v_permlane32_swap_b32_e32 v220, v221
	s_waitcnt lgkmcnt(1)
	v_mfma_f32_32x32x16_bf16 v[80:95], v[244:247], v[108:111], v[80:95]
	s_waitcnt lgkmcnt(0)
	v_mfma_f32_32x32x16_bf16 v[64:79], v[248:251], v[108:111], v[64:79]
	ds_read_b128 v[244:247], v212 offset:32768
	ds_read_b128 v[248:251], v212 offset:40960
	s_waitcnt lgkmcnt(1)
	v_mfma_f32_32x32x16_bf16 v[80:95], v[244:247], v[104:107], v[80:95]
	s_waitcnt lgkmcnt(0)
	v_mfma_f32_32x32x16_bf16 v[64:79], v[248:251], v[104:107], v[64:79]
	ds_read_b128 v[244:247], v213 offset:32768
	ds_read_b128 v[248:251], v213 offset:40960
	s_waitcnt lgkmcnt(1)
	v_mfma_f32_32x32x16_bf16 v[80:95], v[244:247], v[100:103], v[80:95]
	s_waitcnt lgkmcnt(0)
	v_mfma_f32_32x32x16_bf16 v[64:79], v[248:251], v[100:103], v[64:79]
	ds_read_b128 v[244:247], v214 offset:32768
	ds_read_b128 v[248:251], v214 offset:40960
	v_cvt_pk_bf16_f32 v160, v160, v175
	v_cvt_pk_bf16_f32 v161, v161, v174
	v_cvt_pk_bf16_f32 v162, v162, v173
	v_cvt_pk_bf16_f32 v163, v163, v172
	v_cvt_pk_bf16_f32 v164, v164, v171
	v_cvt_pk_bf16_f32 v165, v165, v170
	s_waitcnt lgkmcnt(1)
	v_mfma_f32_32x32x16_bf16 v[80:95], v[244:247], v[96:99], v[80:95]
	v_cvt_pk_bf16_f32 v166, v166, v169
	v_cvt_pk_bf16_f32 v167, v167, v168
	v_cvt_pk_bf16_f32 v168, v224, v225
	v_cvt_pk_bf16_f32 v169, v226, v227
	v_cvt_pk_bf16_f32 v170, v228, v222
	v_cvt_pk_bf16_f32 v171, v223, v229
	v_cvt_pk_bf16_f32 v172, v231, v232
	s_waitcnt lgkmcnt(0)
	v_mfma_f32_32x32x16_bf16 v[64:79], v[248:251], v[96:99], v[64:79]
	v_cvt_pk_bf16_f32 v173, v233, v234
	v_cvt_pk_bf16_f32 v174, v235, v236
	v_cvt_pk_bf16_f32 v175, v237, v238
	v_permlane32_swap_b32_e32 v160, v162
	v_permlane32_swap_b32_e32 v161, v163
	v_permlane32_swap_b32_e32 v164, v166
	v_permlane32_swap_b32_e32 v165, v167
	v_permlane32_swap_b32_e32 v168, v170
	v_permlane32_swap_b32_e32 v169, v171
	v_permlane32_swap_b32_e32 v172, v174
	v_permlane32_swap_b32_e32 v173, v175
	s_waitcnt vmcnt(0)
	ds_write_b128 v203, v[152:155] offset:49152
	ds_write_b128 v206, v[156:159] offset:49152
	s_cmp_ge_u32 s16, s15
	s_cselect_b64 s[10:11], -1, 0
	s_and_b64 vcc, exec, s[10:11]
	s_cbranch_vccnz .LBB0_841
	v_add_co_u32_e32 v128, vcc, 0xffffc000, v194
	s_nop 1
	v_addc_co_u32_e32 v129, vcc, -1, v195, vcc
	v_add_co_u32_e32 v132, vcc, 0xfeefc000, v194
	s_nop 1
	v_addc_co_u32_e32 v133, vcc, -1, v195, vcc
	v_add_co_u32_e32 v140, vcc, 0xfef00000, v194
	global_load_dwordx4 v[128:131], v[128:129], off
	s_nop 0
	global_load_dwordx4 v[132:135], v[132:133], off
	v_addc_co_u32_e32 v141, vcc, -1, v195, vcc
	global_load_dwordx4 v[136:139], v[194:195], off
	s_nop 0
	global_load_dwordx4 v[140:143], v[140:141], off
; #define SBAR() __builtin_amdgcn_sched_barrier(0)
; DI void partialSM(f32x16& p0, f32x16& p1, float& m_reg, float& mn, float& alpha) {
;   constexpr float C = SCALE * 1.4426950408889634f;
;   float pmax = p0[0]; for (int r = 1; r < 16; ++r) pmax = fmaxf(pmax, p0[r]); for (int r = 0; r < 16; ++r) pmax = fmaxf(pmax, p1[r]);
;   { auto rr = __builtin_amdgcn_permlane32_swap(__float_as_uint(pmax), __float_as_uint(pmax), false, false);
;     pmax = fmaxf(__uint_as_float(rr[0]), __uint_as_float(rr[1])); }
;   if (__builtin_expect(__all(pmax - m_reg <= THR / SCALE), 1)) { mn = m_reg; alpha = 1.f; }
;   else { mn = fmaxf(m_reg, pmax); alpha = __builtin_amdgcn_exp2f((m_reg - mn) * C); m_reg = mn; }
;   float mnC = -mn * C;
;   for (int r = 0; r < 16; ++r) p0[r] = fmaf(p0[r], C, mnC); for (int r = 0; r < 16; ++r) p1[r] = fmaf(p1[r], C, mnC);
;   for (int r = 0; r < 16; ++r) p0[r] = __builtin_amdgcn_exp2f(p0[r]);
; }
; template <int D0> DI void pv_one(f32x16& od, int vb, bf16x8 pa0, bf16x8 pa1, bf16x8 pa2, bf16x8 pa3) {
;   const s16x4 l0 = tr_read<v_rd_off(D0, 0, 0)>(vb), h0 = tr_read<v_rd_off(D0, 0, 1)>(vb), l1 = tr_read<v_rd_off(D0, 1, 0)>(vb), h1 = tr_read<v_rd_off(D0, 1, 1)>(vb);
;   const s16x4 l2 = tr_read<v_rd_off(D0, 2, 0)>(vb), h2 = tr_read<v_rd_off(D0, 2, 1)>(vb), l3 = tr_read<v_rd_off(D0, 3, 0)>(vb), h3 = tr_read<v_rd_off(D0, 3, 1)>(vb);
;   asm volatile("s_waitcnt lgkmcnt(0)" ::: "memory"); SBAR();
;     ...
;   od = __builtin_amdgcn_mfma_f32_32x32x16_bf16(pa0, PK(l0, h0), od, 0, 0, 0);
;   od = __builtin_amdgcn_mfma_f32_32x32x16_bf16(pa1, PK(l1, h1), od, 0, 0, 0);
;   od = __builtin_amdgcn_mfma_f32_32x32x16_bf16(pa2, PK(l2, h2), od, 0, 0, 0);
;   od = __builtin_amdgcn_mfma_f32_32x32x16_bf16(pa3, PK(l3, h3), od, 0, 0, 0);
;     ...
; }
; DI void pv_d0(f32x16* o, int vb, bf16x8 pa0, bf16x8 pa1, bf16x8 pa2, bf16x8 pa3) {
;   pv_one<0>(o[0], vb, pa0, pa1, pa2, pa3); pv_one<1>(o[1], vb, pa0, pa1, pa2, pa3); pv_one<2>(o[2], vb, pa0, pa1, pa2, pa3); pv_one<3>(o[3], vb, pa0, pa1, pa2, pa3);
; }
.LBB0_841:
	ds_read_b64_tr_b16 v[232:233], v201 offset:0
	ds_read_b64_tr_b16 v[234:235], v201 offset:0x800
	ds_read_b64_tr_b16 v[236:237], v201 offset:0x1000
	ds_read_b64_tr_b16 v[238:239], v201 offset:0x1800
	ds_read_b64_tr_b16 v[240:241], v201 offset:0x2000
	ds_read_b64_tr_b16 v[242:243], v201 offset:0x2800
	ds_read_b64_tr_b16 v[244:245], v201 offset:0x3000
	ds_read_b64_tr_b16 v[246:247], v201 offset:0x3800
	s_waitcnt lgkmcnt(6)
	s_nop 0
	v_mfma_f32_32x32x16_bf16 v[0:15], v[160:163], v[232:235], v[0:15]
	ds_read_b64_tr_b16 v[232:233], v201 offset:0x200
	ds_read_b64_tr_b16 v[234:235], v201 offset:0xa00
	s_waitcnt lgkmcnt(6)
	v_mfma_f32_32x32x16_bf16 v[0:15], v[164:167], v[236:239], v[0:15]
	ds_read_b64_tr_b16 v[236:237], v201 offset:0x1200
	ds_read_b64_tr_b16 v[238:239], v201 offset:0x1a00
	s_waitcnt lgkmcnt(6)
	v_mfma_f32_32x32x16_bf16 v[0:15], v[168:171], v[240:243], v[0:15]
	ds_read_b64_tr_b16 v[240:241], v201 offset:0x2200
	ds_read_b64_tr_b16 v[242:243], v201 offset:0x2a00
	s_waitcnt lgkmcnt(6)
	v_mfma_f32_32x32x16_bf16 v[0:15], v[172:175], v[244:247], v[0:15]
	ds_read_b64_tr_b16 v[244:245], v201 offset:0x3200
	ds_read_b64_tr_b16 v[246:247], v201 offset:0x3a00
	s_waitcnt lgkmcnt(6)
	v_mfma_f32_32x32x16_bf16 v[48:63], v[160:163], v[232:235], v[48:63]
	ds_read_b64_tr_b16 v[232:233], v201 offset:0x400
	ds_read_b64_tr_b16 v[234:235], v201 offset:0xc00
	s_waitcnt lgkmcnt(6)
	v_mfma_f32_32x32x16_bf16 v[48:63], v[164:167], v[236:239], v[48:63]
	ds_read_b64_tr_b16 v[236:237], v201 offset:0x1400
	ds_read_b64_tr_b16 v[238:239], v201 offset:0x1c00
	s_waitcnt lgkmcnt(6)
	v_mfma_f32_32x32x16_bf16 v[48:63], v[168:171], v[240:243], v[48:63]
	ds_read_b64_tr_b16 v[240:241], v201 offset:0x2400
	ds_read_b64_tr_b16 v[242:243], v201 offset:0x2c00
	s_waitcnt lgkmcnt(6)
	v_mfma_f32_32x32x16_bf16 v[48:63], v[172:175], v[244:247], v[48:63]
	ds_read_b64_tr_b16 v[244:245], v201 offset:0x3400
	ds_read_b64_tr_b16 v[246:247], v201 offset:0x3c00
	s_waitcnt lgkmcnt(6)
	v_mfma_f32_32x32x16_bf16 v[32:47], v[160:163], v[232:235], v[32:47]
	ds_read_b64_tr_b16 v[232:233], v201 offset:0x600
	ds_read_b64_tr_b16 v[234:235], v201 offset:0xe00
	s_waitcnt lgkmcnt(6)
	v_mfma_f32_32x32x16_bf16 v[32:47], v[164:167], v[236:239], v[32:47]
	ds_read_b64_tr_b16 v[236:237], v201 offset:0x1600
	ds_read_b64_tr_b16 v[238:239], v201 offset:0x1e00
	s_waitcnt lgkmcnt(6)
	v_mfma_f32_32x32x16_bf16 v[32:47], v[168:171], v[240:243], v[32:47]
	ds_read_b64_tr_b16 v[240:241], v201 offset:0x2600
	ds_read_b64_tr_b16 v[242:243], v201 offset:0x2e00
	s_waitcnt lgkmcnt(6)
	v_mfma_f32_32x32x16_bf16 v[32:47], v[172:175], v[244:247], v[32:47]
	ds_read_b64_tr_b16 v[244:245], v201 offset:0x3600
	ds_read_b64_tr_b16 v[246:247], v201 offset:0x3e00
	s_waitcnt lgkmcnt(6)
	v_mfma_f32_32x32x16_bf16 v[16:31], v[160:163], v[232:235], v[16:31]
	v_max_f32_e32 v160, v81, v81
	v_max_f32_e32 v161, v80, v80
	v_max_f32_e32 v160, v161, v160
	v_max3_f32 v160, v160, v82, v83
	v_max3_f32 v160, v160, v84, v85
	v_max3_f32 v160, v160, v86, v87
	v_max3_f32 v160, v160, v88, v89
	v_max3_f32 v160, v160, v90, v91
	v_max3_f32 v160, v160, v92, v93
	s_waitcnt lgkmcnt(4)
	v_mfma_f32_32x32x16_bf16 v[16:31], v[164:167], v[236:239], v[16:31]
	v_max3_f32 v160, v160, v94, v95
	v_max3_f32 v160, v160, v64, v65
	v_max3_f32 v160, v160, v66, v67
	v_max3_f32 v160, v160, v68, v69
	v_max3_f32 v160, v160, v70, v71
	v_max3_f32 v160, v160, v72, v73
	v_max3_f32 v160, v160, v74, v75
	v_max3_f32 v160, v160, v76, v77
	s_waitcnt lgkmcnt(2)
	v_mfma_f32_32x32x16_bf16 v[16:31], v[168:171], v[240:243], v[16:31]
	v_max3_f32 v160, v160, v78, v79
	v_mov_b32_e32 v161, v160
	s_nop 1
	v_permlane32_swap_b32_e32 v160, v161
	v_max_f32_e32 v161, v161, v161
	v_max_f32_e32 v160, v160, v160
	v_max_f32_e32 v160, v160, v161
	v_sub_f32_e32 v161, v160, v219
	v_cmp_ge_f32_e32 vcc, s95, v161
	v_max_f32_e32 v161, v219, v219
	v_max_f32_e32 v161, v161, v160
	s_waitcnt lgkmcnt(0)
	v_mfma_f32_32x32x16_bf16 v[16:31], v[172:175], v[244:247], v[16:31]
	v_sub_f32_e32 v160, v219, v161
	v_mul_f32_e32 v160, 0x3e0293ee, v160
	v_exp_f32_e32 v160, v160
	s_cmp_eq_u64 vcc, exec
	s_cselect_b64 s[0:1], -1, 0
	s_barrier
	s_waitcnt vmcnt(4)
	v_cndmask_b32_e64 v160, v160, 1.0, s[0:1]
	v_cmp_gt_f32_e32 vcc, 1.0, v160
	ds_write_b128 v204, v[144:147] offset:16384
	ds_write_b128 v205, v[148:151] offset:16384
	s_cbranch_vccz .LBB0_845
	s_and_saveexec_b64 s[12:13], s[4:5]
	ds_write_b32 v199, v160 offset:128
	s_or_b64 exec, exec, s[12:13]
	s_waitcnt lgkmcnt(0)
	v_add_u32_e32 v156, v198, v180
	ds_read_b128 v[144:147], v156 offset:224
	ds_read_b128 v[148:151], v156 offset:192
	ds_read_b128 v[152:155], v156 offset:160
	ds_read_b128 v[156:159], v156 offset:128
	s_waitcnt lgkmcnt(3)
	v_pk_mul_f32 v[12:13], v[12:13], v[144:145]
	s_waitcnt lgkmcnt(2)
	v_pk_mul_f32 v[8:9], v[8:9], v[148:149]
	s_waitcnt lgkmcnt(1)
	v_pk_mul_f32 v[4:5], v[4:5], v[152:153]
	v_pk_mul_f32 v[14:15], v[14:15], v[146:147]
	v_pk_mul_f32 v[10:11], v[10:11], v[150:151]
	v_pk_mul_f32 v[6:7], v[6:7], v[154:155]
	s_waitcnt lgkmcnt(0)
	v_pk_mul_f32 v[2:3], v[2:3], v[158:159]
	v_pk_mul_f32 v[0:1], v[0:1], v[156:157]
	v_pk_mul_f32 v[60:61], v[60:61], v[144:145]
	v_pk_mul_f32 v[56:57], v[56:57], v[148:149]
	v_pk_mul_f32 v[52:53], v[52:53], v[152:153]
	v_pk_mul_f32 v[62:63], v[62:63], v[146:147]
	v_pk_mul_f32 v[58:59], v[58:59], v[150:151]
	v_pk_mul_f32 v[54:55], v[54:55], v[154:155]
	v_pk_mul_f32 v[50:51], v[50:51], v[158:159]
	v_pk_mul_f32 v[48:49], v[48:49], v[156:157]
	v_pk_mul_f32 v[44:45], v[44:45], v[144:145]
	v_pk_mul_f32 v[40:41], v[40:41], v[148:149]
	v_pk_mul_f32 v[36:37], v[36:37], v[152:153]
	v_pk_mul_f32 v[46:47], v[46:47], v[146:147]
	v_pk_mul_f32 v[42:43], v[42:43], v[150:151]
	v_pk_mul_f32 v[38:39], v[38:39], v[154:155]
	v_pk_mul_f32 v[34:35], v[34:35], v[158:159]
	v_pk_mul_f32 v[32:33], v[32:33], v[156:157]
	v_pk_mul_f32 v[28:29], v[28:29], v[144:145]
	v_pk_mul_f32 v[24:25], v[24:25], v[148:149]
	v_pk_mul_f32 v[20:21], v[20:21], v[152:153]
	v_pk_mul_f32 v[30:31], v[30:31], v[146:147]
	v_pk_mul_f32 v[26:27], v[26:27], v[150:151]
	v_pk_mul_f32 v[22:23], v[22:23], v[154:155]
	v_pk_mul_f32 v[18:19], v[18:19], v[158:159]
	v_pk_mul_f32 v[16:17], v[16:17], v[156:157]
; #define SBAR() __builtin_amdgcn_sched_barrier(0)
; #define SLOAD(i, k0) do { sr_[i].vs0 = ld8(&Vh[(long)((k0) + sr) * LDK + sc]); sr_[i].vs1 = ld8(&Vh[(long)((k0) + 32 + sr) * LDK + sc]); \
;     sr_[i].ks0 = ld8(&Kh[(long)((k0) + sr) * LDK + sc]); sr_[i].ks1 = ld8(&Kh[(long)((k0) + 32 + sr) * LDK + sc]); } while (0)
; #define SWAIT() asm volatile("s_waitcnt vmcnt(4)" ::: "memory")
; DI void partialSM(f32x16& p0, f32x16& p1, float& m_reg, float& mn, float& alpha) {
;     ...
;   if (__builtin_expect(__all(pmax - m_reg <= THR / SCALE), 1)) { mn = m_reg; alpha = 1.f; }
;   else { mn = fmaxf(m_reg, pmax); alpha = __builtin_amdgcn_exp2f((m_reg - mn) * C); m_reg = mn; }
;   float mnC = -mn * C;
;   for (int r = 0; r < 16; ++r) p0[r] = fmaf(p0[r], C, mnC); for (int r = 0; r < 16; ++r) p1[r] = fmaf(p1[r], C, mnC);
;   for (int r = 0; r < 16; ++r) p0[r] = __builtin_amdgcn_exp2f(p0[r]);
; }
; DI void finishSM(f32x16& p0, f32x16& p1, float alpha, float& l_reg, bf16x8& pa0, bf16x8& pa1, bf16x8& pa2, bf16x8& pa3) {
;   for (int r = 0; r < 16; ++r) p1[r] = __builtin_amdgcn_exp2f(p1[r]);
;   float ps = 0; for (int r = 0; r < 16; ++r) ps += p0[r]; for (int r = 0; r < 16; ++r) ps += p1[r];
;   { auto rr = __builtin_amdgcn_permlane32_swap(__float_as_uint(ps), __float_as_uint(ps), false, false);
;     ps = __uint_as_float(rr[0]) + __uint_as_float(rr[1]); }
;   l_reg = l_reg * alpha + ps;
; DI void attn_dense_body(const bf16_t* __restrict__ Qb, const bf16_t* __restrict__ Kh, const bf16_t* __restrict__ Vh, ...
;     ...
;   for (int j = 1; j + 1 < NT; j += 2) {
;     SBAR(); qkt(pB0, pB1, (bf16_t*)((char*)K_lds + SHM_K), qr, r32, hi);
;     finishSM(pA0, pA1, alA, l_reg, pa0, pa1, pa2, pa3); SBAR();
;     SLOAD(SO, (j + 2) * KVBLK); SBAR();
;     pv_d0(o, vb0, pa0, pa1, pa2, pa3); partialSM(pB0, pB1, m_reg, mnB, alB);
;     __syncthreads(); SWAIT(); SWRITE(0, SE);
;     RESC(alB); __syncthreads();
;     SBAR(); qkt(pA0, pA1, K_lds, qr, r32, hi);
;     finishSM(pB0, pB1, alB, l_reg, pa0, pa1, pa2, pa3); SBAR();
;     if (j + 3 < NT) SLOAD(SE, (j + 3) * KVBLK); SBAR();
;     pv_d0(o, vb0 + (int)SHM_V, pa0, pa1, pa2, pa3); partialSM(pA0, pA1, m_reg, mnA, alA);
;     __syncthreads(); SWAIT(); SWRITE(1, SO);
;     RESC(alA); __syncthreads();
;   }
.LBB0_845:
	v_cndmask_b32_e64 v168, v161, v219, s[0:1]
	v_mul_f32_e32 v144, 0xbe0293ee, v168
	v_mov_b32_e32 v145, v144
	v_fmamk_f32 v80, v80, 0x3e0293ee, v144
	v_fmamk_f32 v81, v81, 0x3e0293ee, v144
	v_fmamk_f32 v82, v82, 0x3e0293ee, v144
	v_fmamk_f32 v83, v83, 0x3e0293ee, v144
	v_fmamk_f32 v84, v84, 0x3e0293ee, v144
	v_fmamk_f32 v85, v85, 0x3e0293ee, v144
	v_fmamk_f32 v86, v86, 0x3e0293ee, v144
	v_fmamk_f32 v87, v87, 0x3e0293ee, v144
	v_fmamk_f32 v88, v88, 0x3e0293ee, v144
	v_fmamk_f32 v89, v89, 0x3e0293ee, v144
	v_fmamk_f32 v90, v90, 0x3e0293ee, v144
	v_fmamk_f32 v91, v91, 0x3e0293ee, v144
	v_fmamk_f32 v92, v92, 0x3e0293ee, v144
	v_fmamk_f32 v93, v93, 0x3e0293ee, v144
	v_fmamk_f32 v94, v94, 0x3e0293ee, v144
	v_fmac_f32_e32 v145, 0x3e0293ee, v95
	v_exp_f32_e32 v161, v80
	v_exp_f32_e32 v175, v81
	v_exp_f32_e32 v162, v82
	v_exp_f32_e32 v219, v83
	v_exp_f32_e32 v174, v84
	v_exp_f32_e32 v222, v85
	v_exp_f32_e32 v163, v86
	v_exp_f32_e32 v173, v87
	v_exp_f32_e32 v164, v88
	v_exp_f32_e32 v171, v89
	v_exp_f32_e32 v165, v90
	v_exp_f32_e32 v172, v91
	v_exp_f32_e32 v166, v92
	v_exp_f32_e32 v169, v93
	v_exp_f32_e32 v167, v94
	v_exp_f32_e32 v170, v145
	v_pk_fma_f32 v[158:159], v[64:65], s[42:43], v[144:145] op_sel_hi:[1,0,0]
	v_add_f32_e32 v64, v216, v217
	v_fmac_f32_e32 v64, v215, v200
	v_add_f32_e32 v200, v220, v221
	s_mov_b64 s[0:1], 0x10000
	v_pk_fma_f32 v[156:157], v[66:67], s[42:43], v[144:145] op_sel_hi:[1,0,0]
	v_pk_fma_f32 v[152:153], v[68:69], s[42:43], v[144:145] op_sel_hi:[1,0,0]
	v_pk_fma_f32 v[148:149], v[70:71], s[42:43], v[144:145] op_sel_hi:[1,0,0]
	v_pk_fma_f32 v[146:147], v[72:73], s[42:43], v[144:145] op_sel_hi:[1,0,0]
	v_pk_fma_f32 v[154:155], v[74:75], s[42:43], v[144:145] op_sel_hi:[1,0,0]
	v_pk_fma_f32 v[150:151], v[76:77], s[42:43], v[144:145] op_sel_hi:[1,0,0]
	v_pk_fma_f32 v[144:145], v[78:79], s[42:43], v[144:145] op_sel_hi:[1,0,0]
	v_fmac_f32_e32 v200, v64, v218
	v_lshl_add_u64 v[194:195], v[194:195], 0, s[0:1]
	s_add_i32 s16, s16, 2
	s_and_b64 vcc, exec, s[10:11]
	s_waitcnt lgkmcnt(0)
	s_cbranch_vccnz .LBB0_847
	v_mov_b32_e32 v215, v160
	s_branch .LBB0_835
